# attn-B K tile: 4-bit XOR swizzle (conflict-free ds_read_b128) on top of GEMM barrier hand-off trim
# speedup vs baseline: 1.0094x; 1.0025x over previous
.LBB0_673:
	s_lshl_b32 s16, s31, 8
	s_add_u32 s17, s18, s16
	s_addc_u32 s18, s19, 0
	s_add_u32 s78, s17, 0xf000000
	s_addc_u32 s88, s18, 0
	v_and_b32_e32 v2, 15, v36
	v_lshlrev_b32_e32 v38, 4, v159
	s_add_u32 s89, s26, s16
	v_lshlrev_b32_e32 v2, 4, v2
	s_addc_u32 s50, s27, 0
	s_lshl_b32 s17, s10, 13
	v_lshlrev_b32_e32 v5, 6, v159
	v_and_b32_e32 v6, 0x300, v38
	v_bitop3_b32 v2, v2, v36, 48 bitop3:0x78
	v_lshlrev_b32_e32 v37, 1, v159
	s_lshl_b32 s19, s3, 11
	v_and_b32_e32 v5, 0x700, v5
	v_or3_b32 v2, v6, v2, s17
	v_and_or_b32 v5, v38, 48, v5
	v_or_b32_e32 v140, s19, v2
	v_and_or_b32 v2, v37, 64, s17
	v_or3_b32 v142, v2, s19, v5
	v_or_b32_e32 v2, 0x400, v38
	v_lshrrev_b32_e32 v6, 8, v2
	s_movk_i32 s22, 0x700
	v_bitop3_b32 v6, v6, v36, 15 bitop3:0x78
	v_lshrrev_b32_e32 v2, 3, v2
	v_bitop3_b32 v7, v38, s22, v1 bitop3:0xc8
	v_lshlrev_b32_e32 v6, 4, v6
	v_and_b32_e32 v2, 0xc0, v2
	s_lshl_b32 s18, s13, 6
	s_sub_i32 s16, 2, s33
	s_sub_i32 s11, s11, s13
	v_or3_b32 v6, v6, v7, s17
	v_or_b32_e32 v2, s17, v2
	s_or_b32 s17, s19, s17
	s_cmp_lg_u32 0, -1
	v_or_b32_e32 v144, s19, v6
	s_and_b32 s100, s3, 1
	s_lshl_b32 s100, s100, 7
	v_xor_b32_e32 v140, s100, v140
	v_xor_b32_e32 v144, s100, v144
	v_or3_b32 v146, v2, s19, v5
	s_cselect_b32 s19, 0, 0
	s_add_i32 s51, s17, s19
	s_ashr_i32 s19, s18, 31
	s_add_i32 s91, s51, 0x10000
	s_lshl_b64 s[22:23], s[18:19], 8
	s_add_u32 s26, s89, s22
	s_addc_u32 s27, s50, s23
	s_add_u32 s28, s78, s22
	s_mov_b32 m0, s91
	s_addc_u32 s29, s88, s23
	global_load_lds_dwordx4 v140, s[26:27]
	s_mov_b32 m0, s51
	v_cvt_f32_i32_e32 v2, s16
	global_load_lds_dwordx4 v142, s[28:29]
	s_add_i32 m0, s51, 0x10400
	v_exp_f32_e32 v2, v2
	global_load_lds_dwordx4 v144, s[26:27]
	s_add_i32 m0, s51, 0x400
	s_add_u32 s19, s22, 0x4000
	global_load_lds_dwordx4 v146, s[28:29]
	s_addc_u32 s29, s23, 0
	s_add_u32 s26, s89, s19
	s_addc_u32 s27, s50, s29
	s_add_u32 s28, s78, s19
	s_addc_u32 s29, s88, s29
	s_add_i32 m0, s51, 0x14000
	s_add_i32 s19, s51, 0x4000
	global_load_lds_dwordx4 v140, s[26:27]
	s_mov_b32 m0, s19
	v_readfirstlane_b32 s16, v2
	global_load_lds_dwordx4 v142, s[28:29]
	s_add_i32 m0, s51, 0x14400
	v_mov_b32_e32 v141, v3
	global_load_lds_dwordx4 v144, s[26:27]
	s_add_i32 m0, s51, 0x4400
	s_cmp_eq_u32 s10, 1
	global_load_lds_dwordx4 v146, s[28:29]
	s_cselect_b64 s[26:27], -1, 0
	s_cmp_lg_u32 s10, 1
	s_cselect_b64 s[28:29], -1, 0
	s_cmp_lt_i32 s11, 2
	s_cselect_b64 s[38:39], -1, 0
	s_or_b64 s[28:29], s[28:29], s[38:39]
	v_mov_b32_e32 v143, v3
	v_mov_b32_e32 v145, v3
	v_mov_b32_e32 v147, v3
	s_and_b64 vcc, exec, s[28:29]
	s_cbranch_vccnz .LBB0_675
	s_add_u32 s19, s22, 0x8000
	s_addc_u32 s39, s23, 0
	s_add_u32 s22, s89, s19
	s_addc_u32 s23, s50, s39
	s_add_u32 s38, s78, s19
	s_addc_u32 s39, s88, s39
	s_cmp_lg_u32 0, -1
	s_cselect_b32 s19, 0, 0
	s_add_i32 s17, s19, s17
	s_add_i32 m0, s17, 0x18000
	s_add_i32 s19, s17, 0x8000
	v_lshl_add_u64 v[6:7], s[22:23], 0, v[140:141]
	global_load_lds_dwordx4 v[6:7], off
	v_lshl_add_u64 v[6:7], s[38:39], 0, v[142:143]
	s_mov_b32 m0, s19
	s_nop 0
	global_load_lds_dwordx4 v[6:7], off
	v_lshl_add_u64 v[6:7], s[22:23], 0, v[144:145]
	s_add_i32 m0, s17, 0x18400
	s_nop 0
	global_load_lds_dwordx4 v[6:7], off
	v_lshl_add_u64 v[6:7], s[38:39], 0, v[146:147]
	s_add_i32 m0, s17, 0x8400
	s_nop 0
	global_load_lds_dwordx4 v[6:7], off

.LBB0_681:
	v_subrev_u32_e32 v2, s18, v4
	v_cvt_f32_i32_e32 v163, v2
	s_lshr_b32 s19, s16, 16
	s_lshr_b32 s17, s37, 6
	v_lshl_or_b32 v40, s10, 7, v138
	v_mov_b32_e32 v2, s19
	v_cmp_gt_u32_e64 s[40:41], 32, v159
	v_cvt_f32_ubyte0_e32 v6, v160
	v_lshlrev_b32_e32 v39, 8, v160
	v_or_b32_e32 v41, 32, v40
	v_or_b32_e32 v42, 64, v40
	v_or_b32_e32 v43, 0x60, v40
	v_cndmask_b32_e64 v164, 0, v2, s[40:41]
	s_sub_i32 s19, s17, s13
	s_cmp_lt_i32 s19, 0
	s_cselect_b64 vcc, -1, 0
	v_lshlrev_b32_e32 v2, 4, v160
	s_add_i32 s22, 0, 0x10000
	v_and_b32_e32 v2, 0xf0, v2
	v_add_u32_e32 v4, s22, v39
	v_xad_u32 v5, v40, v2, v4
	ds_read_b128 v[44:47], v5
	ds_read_b128 v[48:51], v5 offset:8192
	v_xad_u32 v5, v41, v2, v4
	ds_read_b128 v[52:55], v5
	ds_read_b128 v[56:59], v5 offset:8192
	v_xad_u32 v5, v42, v2, v4
	v_xad_u32 v2, v43, v2, v4
	ds_read_b128 v[60:63], v5
	ds_read_b128 v[64:67], v5 offset:8192
	ds_read_b128 v[68:71], v2
	ds_read_b128 v[72:75], v2 offset:8192
	s_lshr_b32 s22, s19, 16
	v_mov_b32_e32 v4, v3
	v_mov_b32_e32 v5, v3
	v_bitop3_b32 v2, v164, s22, v233 bitop3:0x78
	v_alignbit_b32 v6, 0, v6, 16
	s_pack_ll_b32_b16 s22, 0, 0
	v_cndmask_b32_e64 v118, 0, v6, s[40:41]
	v_mov_b32_e32 v6, s22
	v_cndmask_b32_e64 v119, 0, v6, s[40:41]
	v_mov_b32_e32 v120, v119
	v_mov_b32_e32 v121, v119
	s_nop 1
	v_mfma_f32_32x32x16_bf16 v[4:19], v[118:121], v[2:5], 0
	s_waitcnt lgkmcnt(0)
	v_mfma_f32_32x32x16_bf16 v[20:35], v[44:47], v[102:105], v[4:19]
	v_mfma_f32_32x32x16_bf16 v[4:19], v[48:51], v[102:105], v[4:19]
	v_mfma_f32_32x32x16_bf16 v[20:35], v[52:55], v[106:109], v[20:35]
	v_mfma_f32_32x32x16_bf16 v[4:19], v[56:59], v[106:109], v[4:19]
	v_mfma_f32_32x32x16_bf16 v[20:35], v[60:63], v[110:113], v[20:35]
	v_mfma_f32_32x32x16_bf16 v[4:19], v[64:67], v[110:113], v[4:19]
	v_mfma_f32_32x32x16_bf16 v[20:35], v[68:71], v[114:117], v[20:35]
	v_mfma_f32_32x32x16_bf16 v[4:19], v[72:75], v[114:117], v[4:19]
	s_waitcnt lgkmcnt(0)
	s_barrier
	v_lshlrev_b32_e32 v2, 2, v161
	s_cmp_lg_u32 s17, s13
	v_mul_f32_e64 v148, s16, -2.0
	v_cvt_f32_ubyte0_e32 v165, v2
	s_cbranch_scc1 .LBB0_683
	v_sub_f32_e32 v2, v163, v165
	v_sub_f32_e32 v45, 0x42000000, v2
	v_sub_f32_e32 v49, 0x42080000, v2
	v_sub_f32_e32 v53, 0x42200000, v2
	v_sub_f32_e32 v57, 0x42280000, v2
	v_sub_f32_e32 v61, 0x42400000, v2
	v_sub_f32_e32 v65, 0x42480000, v2
	v_sub_f32_e32 v69, 0x42600000, v2
	v_sub_f32_e32 v73, 0x42680000, v2
	v_max_f32_e64 v44, -v2, 0
	v_max_f32_e32 v46, 0, v45
	v_sub_f32_e32 v45, 1.0, v2
	v_sub_f32_e32 v47, 0x42040000, v2
	v_sub_f32_e32 v48, 2.0, v2
	v_max_f32_e32 v50, 0, v49
	v_sub_f32_e32 v49, 0x40400000, v2
	v_sub_f32_e32 v51, 0x420c0000, v2
	v_sub_f32_e32 v52, 0x41000000, v2
	v_max_f32_e32 v54, 0, v53
	v_sub_f32_e32 v53, 0x41100000, v2
	v_sub_f32_e32 v55, 0x42240000, v2
	v_sub_f32_e32 v56, 0x41200000, v2
	v_max_f32_e32 v58, 0, v57
	v_sub_f32_e32 v57, 0x41300000, v2
	v_sub_f32_e32 v59, 0x422c0000, v2
	v_sub_f32_e32 v60, 0x41800000, v2
	v_max_f32_e32 v62, 0, v61
	v_sub_f32_e32 v61, 0x41880000, v2
	v_sub_f32_e32 v63, 0x42440000, v2
	v_sub_f32_e32 v64, 0x41900000, v2
	v_max_f32_e32 v66, 0, v65
	v_sub_f32_e32 v65, 0x41980000, v2
	v_sub_f32_e32 v67, 0x424c0000, v2
	v_sub_f32_e32 v68, 0x41c00000, v2
	v_max_f32_e32 v70, 0, v69
	v_sub_f32_e32 v69, 0x41c80000, v2
	v_sub_f32_e32 v71, 0x42640000, v2
	v_sub_f32_e32 v72, 0x41d00000, v2
	v_max_f32_e32 v74, 0, v73
	v_sub_f32_e32 v73, 0x41d80000, v2
	v_sub_f32_e32 v2, 0x426c0000, v2
	v_max_f32_e32 v45, 0, v45
	v_max_f32_e32 v47, 0, v47
	v_max_f32_e32 v48, 0, v48
	v_max_f32_e32 v49, 0, v49
	v_max_f32_e32 v51, 0, v51
	v_max_f32_e32 v52, 0, v52
	v_max_f32_e32 v53, 0, v53
	v_max_f32_e32 v55, 0, v55
	v_max_f32_e32 v56, 0, v56
	v_max_f32_e32 v57, 0, v57
	v_max_f32_e32 v59, 0, v59
	v_max_f32_e32 v60, 0, v60
	v_max_f32_e32 v61, 0, v61
	v_max_f32_e32 v63, 0, v63
	v_max_f32_e32 v64, 0, v64
	v_max_f32_e32 v65, 0, v65
	v_max_f32_e32 v67, 0, v67
	v_max_f32_e32 v68, 0, v68
	v_max_f32_e32 v69, 0, v69
	v_max_f32_e32 v71, 0, v71
	v_max_f32_e32 v72, 0, v72
	v_max_f32_e32 v73, 0, v73
	v_max_f32_e32 v75, 0, v2
	v_pk_fma_f32 v[34:35], v[72:73], v[148:149], v[34:35] op_sel_hi:[1,0,1]
	v_pk_fma_f32 v[32:33], v[68:69], v[148:149], v[32:33] op_sel_hi:[1,0,1]
	v_pk_fma_f32 v[30:31], v[64:65], v[148:149], v[30:31] op_sel_hi:[1,0,1]
	v_pk_fma_f32 v[28:29], v[60:61], v[148:149], v[28:29] op_sel_hi:[1,0,1]
	v_pk_fma_f32 v[26:27], v[56:57], v[148:149], v[26:27] op_sel_hi:[1,0,1]
	v_pk_fma_f32 v[24:25], v[52:53], v[148:149], v[24:25] op_sel_hi:[1,0,1]
	v_pk_fma_f32 v[22:23], v[48:49], v[148:149], v[22:23] op_sel_hi:[1,0,1]
	v_pk_fma_f32 v[20:21], v[44:45], v[148:149], v[20:21] op_sel_hi:[1,0,1]
	v_pk_fma_f32 v[18:19], v[74:75], v[148:149], v[18:19] op_sel_hi:[1,0,1]
	v_pk_fma_f32 v[16:17], v[70:71], v[148:149], v[16:17] op_sel_hi:[1,0,1]
	v_pk_fma_f32 v[14:15], v[66:67], v[148:149], v[14:15] op_sel_hi:[1,0,1]
	v_pk_fma_f32 v[12:13], v[62:63], v[148:149], v[12:13] op_sel_hi:[1,0,1]
	v_pk_fma_f32 v[10:11], v[58:59], v[148:149], v[10:11] op_sel_hi:[1,0,1]
	v_pk_fma_f32 v[8:9], v[54:55], v[148:149], v[8:9] op_sel_hi:[1,0,1]
	v_pk_fma_f32 v[6:7], v[50:51], v[148:149], v[6:7] op_sel_hi:[1,0,1]
	v_pk_fma_f32 v[4:5], v[46:47], v[148:149], v[4:5] op_sel_hi:[1,0,1]

.LBB0_696:
	v_lshlrev_b32_e32 v2, 3, v159
	v_and_b32_e32 v4, 0xc0, v38
	v_and_or_b32 v4, v2, 24, v4
	v_and_b32_e32 v5, 32, v37
	v_and_b32_e32 v2, 0x100, v2
	s_cmp_lg_u32 0, -1
	v_add_f32_e32 v170, v22, v23
	v_or3_b32 v2, v4, v5, v2
	s_cselect_b32 s13, 0, 0
	v_fmac_f32_e32 v170, 0, v44
	v_add_u32_e32 v171, s13, v2
	s_cmp_lt_i32 s11, 1
	v_lshlrev_b32_e32 v139, 4, v36
	v_lshl_add_u32 v169, v160, 2, s26
	s_cbranch_scc1 .LBB0_712
	s_cmp_lg_u32 0, -1
	s_cselect_b32 s13, 0, 0
	s_add_i32 s13, s13, 0x10000
	v_and_b32_e32 v2, 0xf0, v139
	v_add_u32_e32 v4, s13, v39
	v_xad_u32 v172, v40, v2, v4
	v_xad_u32 v173, v41, v2, v4
	v_xad_u32 v184, v42, v2, v4
	v_xad_u32 v185, v43, v2, v4
	v_mov_b64_e32 v[68:69], v[20:21]
	v_mov_b64_e32 v[52:53], v[20:21]
	v_mov_b64_e32 v[36:37], v[20:21]
	v_mov_b32_e32 v150, v148
	v_mov_b32_e32 v151, v148
	s_sub_i32 s22, 0, s11
	s_add_i32 s18, s18, s12
	s_lshl_b32 s23, s10, 14
	s_mov_b32 s27, 1
	s_movk_i32 s28, 0xc0
	s_mov_b32 s29, 0xc000
	v_mov_b64_e32 v[66:67], v[18:19]
	v_mov_b64_e32 v[64:65], v[16:17]
	v_mov_b64_e32 v[62:63], v[14:15]
	v_mov_b64_e32 v[60:61], v[12:13]
	v_mov_b64_e32 v[58:59], v[10:11]
	v_mov_b64_e32 v[56:57], v[8:9]
	v_mov_b64_e32 v[54:55], v[6:7]
	v_mov_b64_e32 v[50:51], v[18:19]
	v_mov_b64_e32 v[48:49], v[16:17]
	v_mov_b64_e32 v[46:47], v[14:15]
	v_mov_b64_e32 v[44:45], v[12:13]
	v_mov_b64_e32 v[42:43], v[10:11]
	v_mov_b64_e32 v[40:41], v[8:9]
	v_mov_b64_e32 v[38:39], v[6:7]
	v_mov_b64_e32 v[34:35], v[18:19]
	v_mov_b64_e32 v[32:33], v[16:17]
	v_mov_b64_e32 v[30:31], v[14:15]
	v_mov_b64_e32 v[28:29], v[12:13]
	v_mov_b64_e32 v[26:27], v[10:11]
	v_mov_b64_e32 v[24:25], v[8:9]
	v_mov_b64_e32 v[22:23], v[6:7]

	.amdhsa_kernel _Z6mk_fwd4Args
		.amdhsa_group_segment_fixed_size 0
		.amdhsa_private_segment_fixed_size 0
		.amdhsa_kernarg_size 456
		.amdhsa_user_sgpr_count 2
		.amdhsa_user_sgpr_dispatch_ptr 0
		.amdhsa_user_sgpr_queue_ptr 0
		.amdhsa_user_sgpr_kernarg_segment_ptr 1
		.amdhsa_user_sgpr_dispatch_id 0
		.amdhsa_user_sgpr_kernarg_preload_length 0
		.amdhsa_user_sgpr_kernarg_preload_offset 0
		.amdhsa_user_sgpr_private_segment_size 0
		.amdhsa_uses_dynamic_stack 0
		.amdhsa_enable_private_segment 0
		.amdhsa_system_sgpr_workgroup_id_x 1
		.amdhsa_system_sgpr_workgroup_id_y 0
		.amdhsa_system_sgpr_workgroup_id_z 0
		.amdhsa_system_sgpr_workgroup_info 0
		.amdhsa_system_vgpr_workitem_id 0
		.amdhsa_next_free_vgpr 256
		.amdhsa_next_free_sgpr 102
		.amdhsa_accum_offset 256
		.amdhsa_reserve_vcc 1
		.amdhsa_float_round_mode_32 0
		.amdhsa_float_round_mode_16_64 0
		.amdhsa_float_denorm_mode_32 3
		.amdhsa_float_denorm_mode_16_64 3
		.amdhsa_dx10_clamp 1
		.amdhsa_ieee_mode 1
		.amdhsa_fp16_overflow 0
		.amdhsa_tg_split 0
		.amdhsa_exception_fp_ieee_invalid_op 0
		.amdhsa_exception_fp_denorm_src 0
		.amdhsa_exception_fp_ieee_div_zero 0
		.amdhsa_exception_fp_ieee_overflow 0
		.amdhsa_exception_fp_ieee_underflow 0
		.amdhsa_exception_fp_ieee_inexact 0
		.amdhsa_exception_int_div_zero 0
	.end_amdhsa_kernel

amdhsa.kernels:
  - .agpr_count:     0
    .args:
      - .offset:         0
        .size:           200
        .value_kind:     by_value
      - .offset:         200
        .size:           4
        .value_kind:     hidden_block_count_x
      - .offset:         204
        .size:           4
        .value_kind:     hidden_block_count_y
      - .offset:         208
        .size:           4
        .value_kind:     hidden_block_count_z
      - .offset:         212
        .size:           2
        .value_kind:     hidden_group_size_x
      - .offset:         214
        .size:           2
        .value_kind:     hidden_group_size_y
      - .offset:         216
        .size:           2
        .value_kind:     hidden_group_size_z
      - .offset:         218
        .size:           2
        .value_kind:     hidden_remainder_x
      - .offset:         220
        .size:           2
        .value_kind:     hidden_remainder_y
      - .offset:         222
        .size:           2
        .value_kind:     hidden_remainder_z
      - .offset:         240
        .size:           8
        .value_kind:     hidden_global_offset_x
      - .offset:         248
        .size:           8
        .value_kind:     hidden_global_offset_y
      - .offset:         256
        .size:           8
        .value_kind:     hidden_global_offset_z
      - .offset:         264
        .size:           2
        .value_kind:     hidden_grid_dims
      - .offset:         320
        .size:           4
        .value_kind:     hidden_dynamic_lds_size
    .group_segment_fixed_size: 0
    .kernarg_segment_align: 8
    .kernarg_segment_size: 456
    .language:       OpenCL C
    .language_version:
      - 2
      - 0
    .max_flat_workgroup_size: 512
    .name:           _Z6mk_fwd4Args
    .private_segment_fixed_size: 0
    .sgpr_count:     108
    .sgpr_spill_count: 386
    .symbol:         _Z6mk_fwd4Args.kd
    .uniform_work_group_size: 1
    .uses_dynamic_stack: false
    .vgpr_count:     256
    .vgpr_spill_count: 0
    .wavefront_size: 64
